# prologue weight-copy items: 32 loads in flight per 64x32 tile instead of 4 serialized rounds of 8
# speedup vs baseline: 1.0052x; 1.0052x over previous
.LBB0_33:
	v_lshl_add_u64 v[38:39], v[36:37], 0, s[6:7]
	v_lshl_add_u64 v[40:41], v[34:35], 0, s[6:7]
	v_lshl_add_u64 v[80:81], v[32:33], 0, s[6:7]
	v_lshl_add_u64 v[82:83], v[30:31], 0, s[6:7]
	v_lshl_add_u64 v[84:85], v[8:9], 0, s[6:7]
	v_lshl_add_u64 v[86:87], v[6:7], 0, s[6:7]
	v_lshl_add_u64 v[88:89], v[4:5], 0, s[6:7]
	v_lshl_add_u64 v[90:91], v[2:3], 0, s[6:7]
	global_load_dword v148, v[38:39], off nt
	s_nop 0
	global_load_dword v149, v[40:41], off nt
	global_load_dword v150, v[80:81], off nt
	s_nop 0
	global_load_dword v151, v[82:83], off nt
	global_load_dword v152, v[84:85], off nt
	global_load_dword v153, v[86:87], off nt
	global_load_dword v154, v[88:89], off nt
	s_nop 0
	global_load_dword v155, v[90:91], off nt
	s_add_u32 s6, s6, 0x10000
	s_addc_u32 s7, s7, 0
	v_lshl_add_u64 v[38:39], v[36:37], 0, s[6:7]
	v_lshl_add_u64 v[40:41], v[34:35], 0, s[6:7]
	v_lshl_add_u64 v[80:81], v[32:33], 0, s[6:7]
	v_lshl_add_u64 v[82:83], v[30:31], 0, s[6:7]
	v_lshl_add_u64 v[84:85], v[8:9], 0, s[6:7]
	v_lshl_add_u64 v[86:87], v[6:7], 0, s[6:7]
	v_lshl_add_u64 v[88:89], v[4:5], 0, s[6:7]
	v_lshl_add_u64 v[90:91], v[2:3], 0, s[6:7]
	global_load_dword v156, v[38:39], off nt
	s_nop 0
	global_load_dword v157, v[40:41], off nt
	global_load_dword v158, v[80:81], off nt
	s_nop 0
	global_load_dword v159, v[82:83], off nt
	global_load_dword v160, v[84:85], off nt
	global_load_dword v161, v[86:87], off nt
	global_load_dword v162, v[88:89], off nt
	s_nop 0
	global_load_dword v163, v[90:91], off nt
	s_add_u32 s6, s6, 0x10000
	s_addc_u32 s7, s7, 0
	v_lshl_add_u64 v[38:39], v[36:37], 0, s[6:7]
	v_lshl_add_u64 v[40:41], v[34:35], 0, s[6:7]
	v_lshl_add_u64 v[80:81], v[32:33], 0, s[6:7]
	v_lshl_add_u64 v[82:83], v[30:31], 0, s[6:7]
	v_lshl_add_u64 v[84:85], v[8:9], 0, s[6:7]
	v_lshl_add_u64 v[86:87], v[6:7], 0, s[6:7]
	v_lshl_add_u64 v[88:89], v[4:5], 0, s[6:7]
	v_lshl_add_u64 v[90:91], v[2:3], 0, s[6:7]
	global_load_dword v164, v[38:39], off nt
	s_nop 0
	global_load_dword v165, v[40:41], off nt
	global_load_dword v166, v[80:81], off nt
	s_nop 0
	global_load_dword v167, v[82:83], off nt
	global_load_dword v168, v[84:85], off nt
	global_load_dword v169, v[86:87], off nt
	global_load_dword v170, v[88:89], off nt
	s_nop 0
	global_load_dword v171, v[90:91], off nt
	s_add_u32 s6, s6, 0x10000
	s_addc_u32 s7, s7, 0
	v_lshl_add_u64 v[38:39], v[36:37], 0, s[6:7]
	v_lshl_add_u64 v[40:41], v[34:35], 0, s[6:7]
	v_lshl_add_u64 v[80:81], v[32:33], 0, s[6:7]
	v_lshl_add_u64 v[82:83], v[30:31], 0, s[6:7]
	v_lshl_add_u64 v[84:85], v[8:9], 0, s[6:7]
	v_lshl_add_u64 v[86:87], v[6:7], 0, s[6:7]
	v_lshl_add_u64 v[88:89], v[4:5], 0, s[6:7]
	v_lshl_add_u64 v[90:91], v[2:3], 0, s[6:7]
	global_load_dword v172, v[38:39], off nt
	s_nop 0
	global_load_dword v173, v[40:41], off nt
	global_load_dword v174, v[80:81], off nt
	s_nop 0
	global_load_dword v175, v[82:83], off nt
	global_load_dword v176, v[84:85], off nt
	global_load_dword v177, v[86:87], off nt
	global_load_dword v178, v[88:89], off nt
	s_nop 0
	global_load_dword v179, v[90:91], off nt
	s_add_u32 s6, s6, 0x10000
	s_addc_u32 s7, s7, 0
	v_add_u32_e32 v83, 0x400, v10
	s_waitcnt vmcnt(30)
	ds_write2_b32 v10, v148, v149 offset1:66
	s_waitcnt vmcnt(28)
	ds_write2_b32 v10, v150, v151 offset0:132 offset1:198
	s_waitcnt vmcnt(26)
	ds_write2_b32 v83, v152, v153 offset0:8 offset1:74
	s_waitcnt vmcnt(24)
	ds_write2_b32 v83, v154, v155 offset0:140 offset1:206
	v_add_u32_e32 v10, 0x840, v10
	v_add_u32_e32 v83, 0x400, v10
	s_waitcnt vmcnt(22)
	ds_write2_b32 v10, v156, v157 offset1:66
	s_waitcnt vmcnt(20)
	ds_write2_b32 v10, v158, v159 offset0:132 offset1:198
	s_waitcnt vmcnt(18)
	ds_write2_b32 v83, v160, v161 offset0:8 offset1:74
	s_waitcnt vmcnt(16)
	ds_write2_b32 v83, v162, v163 offset0:140 offset1:206
	v_add_u32_e32 v10, 0x840, v10
	v_add_u32_e32 v83, 0x400, v10
	s_waitcnt vmcnt(14)
	ds_write2_b32 v10, v164, v165 offset1:66
	s_waitcnt vmcnt(12)
	ds_write2_b32 v10, v166, v167 offset0:132 offset1:198
	s_waitcnt vmcnt(10)
	ds_write2_b32 v83, v168, v169 offset0:8 offset1:74
	s_waitcnt vmcnt(8)
	ds_write2_b32 v83, v170, v171 offset0:140 offset1:206
	v_add_u32_e32 v10, 0x840, v10
	v_add_u32_e32 v83, 0x400, v10
	s_waitcnt vmcnt(6)
	ds_write2_b32 v10, v172, v173 offset1:66
	s_waitcnt vmcnt(4)
	ds_write2_b32 v10, v174, v175 offset0:132 offset1:198
	s_waitcnt vmcnt(2)
	ds_write2_b32 v83, v176, v177 offset0:8 offset1:74
	s_waitcnt vmcnt(0)
	ds_write2_b32 v83, v178, v179 offset0:140 offset1:206
	v_add_u32_e32 v10, 0x840, v10
	s_waitcnt lgkmcnt(0)
	s_lshl_b32 s6, s81, 5
	s_add_i32 s28, s5, 0xffffb900
	ds_read2_b32 v[6:7], v45 offset1:8
	s_and_b32 s8, s6, 0x3e0
	s_lshl_b64 s[6:7], s[28:29], 1
	ds_read2_b32 v[30:31], v45 offset0:33 offset1:41
	s_add_u32 s6, s79, s6
	s_addc_u32 s7, s80, s7
	v_lshlrev_b32_e32 v10, 1, v12
	ds_read2_b32 v[32:33], v45 offset0:66 offset1:74
	v_lshl_add_u64 v[2:3], s[6:7], 0, v[10:11]
	ds_read2_b32 v[34:35], v45 offset0:99 offset1:107
	v_lshl_add_u64 v[8:9], v[2:3], 0, s[30:31]
	s_waitcnt lgkmcnt(3)
	v_bfe_u32 v2, v6, 16, 1
	v_add3_u32 v2, v6, v2, s53
	s_waitcnt lgkmcnt(2)
	v_bfe_u32 v3, v30, 16, 1
	ds_read2_b32 v[36:37], v45 offset0:132 offset1:140
	v_lshrrev_b32_e32 v2, 16, v2
	v_add3_u32 v3, v30, v3, s53
	ds_read2_b32 v[38:39], v45 offset0:165 offset1:173
	v_and_or_b32 v2, v3, s54, v2
	s_waitcnt lgkmcnt(3)
	v_bfe_u32 v3, v32, 16, 1
	v_add3_u32 v3, v32, v3, s53
	s_waitcnt lgkmcnt(2)
	v_bfe_u32 v4, v34, 16, 1
	ds_read2_b32 v[40:41], v45 offset0:198 offset1:206
	v_lshrrev_b32_e32 v3, 16, v3
	v_add3_u32 v4, v34, v4, s53
	ds_read2_b32 v[80:81], v45 offset0:231 offset1:239
	v_and_or_b32 v3, v4, s54, v3
	s_waitcnt lgkmcnt(3)
	v_bfe_u32 v4, v36, 16, 1
	v_add3_u32 v4, v36, v4, s53
	s_waitcnt lgkmcnt(2)
	v_bfe_u32 v5, v38, 16, 1
	v_lshrrev_b32_e32 v4, 16, v4
	v_add3_u32 v5, v38, v5, s53
	v_and_or_b32 v4, v5, s54, v4
	s_waitcnt lgkmcnt(1)
	v_bfe_u32 v5, v40, 16, 1
	v_add3_u32 v5, v40, v5, s53
	s_waitcnt lgkmcnt(0)
	v_bfe_u32 v6, v80, 16, 1
	v_lshrrev_b32_e32 v5, 16, v5
	v_add3_u32 v6, v80, v6, s53
	v_and_or_b32 v5, v6, s54, v5
	v_or_b32_e32 v6, s8, v44
	v_lshlrev_b32_e32 v10, 11, v6
	v_lshl_add_u64 v[82:83], v[8:9], 0, v[10:11]
	global_store_dwordx4 v[82:83], v[2:5], off
	v_bfe_u32 v6, v81, 16, 1
	v_or_b32_e32 v10, s8, v46
	v_bfe_u32 v2, v7, 16, 1
	v_add3_u32 v2, v7, v2, s53
	v_bfe_u32 v3, v31, 16, 1
	v_lshrrev_b32_e32 v2, 16, v2
	v_add3_u32 v3, v31, v3, s53
	v_and_or_b32 v2, v3, s54, v2
	v_bfe_u32 v3, v33, 16, 1
	v_add3_u32 v3, v33, v3, s53
	v_bfe_u32 v4, v35, 16, 1
	v_lshrrev_b32_e32 v3, 16, v3
	v_add3_u32 v4, v35, v4, s53
	v_and_or_b32 v3, v4, s54, v3
	v_bfe_u32 v4, v37, 16, 1
	v_add3_u32 v4, v37, v4, s53
	v_bfe_u32 v5, v39, 16, 1
	v_lshrrev_b32_e32 v4, 16, v4
	v_add3_u32 v5, v39, v5, s53
	v_and_or_b32 v4, v5, s54, v4
	v_bfe_u32 v5, v41, 16, 1
	v_add3_u32 v5, v41, v5, s53
	v_lshrrev_b32_e32 v5, 16, v5
	v_add3_u32 v6, v81, v6, s53
	v_lshlrev_b32_e32 v10, 11, v10
	v_and_or_b32 v5, v6, s54, v5
	ds_read2_b32 v[6:7], v45 offset0:16 offset1:24
	v_lshl_add_u64 v[30:31], v[8:9], 0, v[10:11]
	global_store_dwordx4 v[30:31], v[2:5], off
	ds_read2_b32 v[30:31], v45 offset0:49 offset1:57
	ds_read2_b32 v[32:33], v45 offset0:82 offset1:90
	ds_read2_b32 v[34:35], v45 offset0:115 offset1:123
	s_waitcnt lgkmcnt(3)
	v_bfe_u32 v2, v6, 16, 1
	v_add3_u32 v2, v6, v2, s53
	s_waitcnt lgkmcnt(2)
	v_bfe_u32 v3, v30, 16, 1
	ds_read2_b32 v[36:37], v45 offset0:148 offset1:156
	v_lshrrev_b32_e32 v2, 16, v2
	v_add3_u32 v3, v30, v3, s53
	ds_read2_b32 v[38:39], v45 offset0:181 offset1:189
	v_and_or_b32 v2, v3, s54, v2
	s_waitcnt lgkmcnt(3)
	v_bfe_u32 v3, v32, 16, 1
	v_add3_u32 v3, v32, v3, s53
	s_waitcnt lgkmcnt(2)
	v_bfe_u32 v4, v34, 16, 1
	ds_read2_b32 v[40:41], v45 offset0:214 offset1:222
	v_lshrrev_b32_e32 v3, 16, v3
	v_add3_u32 v4, v34, v4, s53
	ds_read2_b32 v[80:81], v45 offset0:247 offset1:255
	v_and_or_b32 v3, v4, s54, v3
	s_waitcnt lgkmcnt(3)
	v_bfe_u32 v4, v36, 16, 1
	v_add3_u32 v4, v36, v4, s53
	s_waitcnt lgkmcnt(2)
	v_bfe_u32 v5, v38, 16, 1
	v_lshrrev_b32_e32 v4, 16, v4
	v_add3_u32 v5, v38, v5, s53
	v_and_or_b32 v4, v5, s54, v4
	s_waitcnt lgkmcnt(1)
	v_bfe_u32 v5, v40, 16, 1
	v_add3_u32 v5, v40, v5, s53
	s_waitcnt lgkmcnt(0)
	v_bfe_u32 v6, v80, 16, 1
	v_lshrrev_b32_e32 v5, 16, v5
	v_add3_u32 v6, v80, v6, s53
	v_and_or_b32 v5, v6, s54, v5
	v_or_b32_e32 v6, s8, v47
	v_lshlrev_b32_e32 v10, 11, v6
	v_lshl_add_u64 v[82:83], v[8:9], 0, v[10:11]
	global_store_dwordx4 v[82:83], v[2:5], off
	v_bfe_u32 v6, v81, 16, 1
	v_add3_u32 v6, v81, v6, s53
	v_bfe_u32 v2, v7, 16, 1
	v_add3_u32 v2, v7, v2, s53
	v_bfe_u32 v3, v31, 16, 1
	v_lshrrev_b32_e32 v2, 16, v2
	v_add3_u32 v3, v31, v3, s53
	v_and_or_b32 v2, v3, s54, v2
	v_bfe_u32 v3, v33, 16, 1
	v_add3_u32 v3, v33, v3, s53
	v_bfe_u32 v4, v35, 16, 1
	v_lshrrev_b32_e32 v3, 16, v3
	v_add3_u32 v4, v35, v4, s53
	v_and_or_b32 v3, v4, s54, v3
	v_bfe_u32 v4, v37, 16, 1
	v_add3_u32 v4, v37, v4, s53
	v_bfe_u32 v5, v39, 16, 1
	v_lshrrev_b32_e32 v4, 16, v4
	v_add3_u32 v5, v39, v5, s53
	v_and_or_b32 v4, v5, s54, v4
	v_bfe_u32 v5, v41, 16, 1
	v_add3_u32 v5, v41, v5, s53
	v_lshrrev_b32_e32 v5, 16, v5
	v_and_or_b32 v5, v6, s54, v5
	v_or_b32_e32 v6, s8, v48
	v_lshlrev_b32_e32 v10, 11, v6
	v_lshl_add_u64 v[6:7], v[8:9], 0, v[10:11]
	global_store_dwordx4 v[6:7], v[2:5], off
	s_waitcnt lgkmcnt(0)

.LBB0_43:
	v_lshl_add_u64 v[38:39], v[36:37], 0, s[6:7]
	v_lshl_add_u64 v[40:41], v[34:35], 0, s[6:7]
	v_lshl_add_u64 v[80:81], v[32:33], 0, s[6:7]
	v_lshl_add_u64 v[82:83], v[30:31], 0, s[6:7]
	v_lshl_add_u64 v[84:85], v[8:9], 0, s[6:7]
	v_lshl_add_u64 v[86:87], v[6:7], 0, s[6:7]
	v_lshl_add_u64 v[88:89], v[4:5], 0, s[6:7]
	v_lshl_add_u64 v[90:91], v[2:3], 0, s[6:7]
	global_load_dword v148, v[38:39], off nt
	s_nop 0
	global_load_dword v149, v[40:41], off nt
	global_load_dword v150, v[80:81], off nt
	s_nop 0
	global_load_dword v151, v[82:83], off nt
	global_load_dword v152, v[84:85], off nt
	global_load_dword v153, v[86:87], off nt
	global_load_dword v154, v[88:89], off nt
	s_nop 0
	global_load_dword v155, v[90:91], off nt
	s_add_u32 s6, s6, 0x14000
	s_addc_u32 s7, s7, 0
	v_lshl_add_u64 v[38:39], v[36:37], 0, s[6:7]
	v_lshl_add_u64 v[40:41], v[34:35], 0, s[6:7]
	v_lshl_add_u64 v[80:81], v[32:33], 0, s[6:7]
	v_lshl_add_u64 v[82:83], v[30:31], 0, s[6:7]
	v_lshl_add_u64 v[84:85], v[8:9], 0, s[6:7]
	v_lshl_add_u64 v[86:87], v[6:7], 0, s[6:7]
	v_lshl_add_u64 v[88:89], v[4:5], 0, s[6:7]
	v_lshl_add_u64 v[90:91], v[2:3], 0, s[6:7]
	global_load_dword v156, v[38:39], off nt
	s_nop 0
	global_load_dword v157, v[40:41], off nt
	global_load_dword v158, v[80:81], off nt
	s_nop 0
	global_load_dword v159, v[82:83], off nt
	global_load_dword v160, v[84:85], off nt
	global_load_dword v161, v[86:87], off nt
	global_load_dword v162, v[88:89], off nt
	s_nop 0
	global_load_dword v163, v[90:91], off nt
	s_add_u32 s6, s6, 0x14000
	s_addc_u32 s7, s7, 0
	v_lshl_add_u64 v[38:39], v[36:37], 0, s[6:7]
	v_lshl_add_u64 v[40:41], v[34:35], 0, s[6:7]
	v_lshl_add_u64 v[80:81], v[32:33], 0, s[6:7]
	v_lshl_add_u64 v[82:83], v[30:31], 0, s[6:7]
	v_lshl_add_u64 v[84:85], v[8:9], 0, s[6:7]
	v_lshl_add_u64 v[86:87], v[6:7], 0, s[6:7]
	v_lshl_add_u64 v[88:89], v[4:5], 0, s[6:7]
	v_lshl_add_u64 v[90:91], v[2:3], 0, s[6:7]
	global_load_dword v164, v[38:39], off nt
	s_nop 0
	global_load_dword v165, v[40:41], off nt
	global_load_dword v166, v[80:81], off nt
	s_nop 0
	global_load_dword v167, v[82:83], off nt
	global_load_dword v168, v[84:85], off nt
	global_load_dword v169, v[86:87], off nt
	global_load_dword v170, v[88:89], off nt
	s_nop 0
	global_load_dword v171, v[90:91], off nt
	s_add_u32 s6, s6, 0x14000
	s_addc_u32 s7, s7, 0
	v_lshl_add_u64 v[38:39], v[36:37], 0, s[6:7]
	v_lshl_add_u64 v[40:41], v[34:35], 0, s[6:7]
	v_lshl_add_u64 v[80:81], v[32:33], 0, s[6:7]
	v_lshl_add_u64 v[82:83], v[30:31], 0, s[6:7]
	v_lshl_add_u64 v[84:85], v[8:9], 0, s[6:7]
	v_lshl_add_u64 v[86:87], v[6:7], 0, s[6:7]
	v_lshl_add_u64 v[88:89], v[4:5], 0, s[6:7]
	v_lshl_add_u64 v[90:91], v[2:3], 0, s[6:7]
	global_load_dword v172, v[38:39], off nt
	s_nop 0
	global_load_dword v173, v[40:41], off nt
	global_load_dword v174, v[80:81], off nt
	s_nop 0
	global_load_dword v175, v[82:83], off nt
	global_load_dword v176, v[84:85], off nt
	global_load_dword v177, v[86:87], off nt
	global_load_dword v178, v[88:89], off nt
	s_nop 0
	global_load_dword v179, v[90:91], off nt
	s_add_u32 s6, s6, 0x14000
	s_addc_u32 s7, s7, 0
	v_add_u32_e32 v83, 0x400, v10
	s_waitcnt vmcnt(30)
	ds_write2_b32 v10, v148, v149 offset1:66
	s_waitcnt vmcnt(28)
	ds_write2_b32 v10, v150, v151 offset0:132 offset1:198
	s_waitcnt vmcnt(26)
	ds_write2_b32 v83, v152, v153 offset0:8 offset1:74
	s_waitcnt vmcnt(24)
	ds_write2_b32 v83, v154, v155 offset0:140 offset1:206
	v_add_u32_e32 v10, 0x840, v10
	v_add_u32_e32 v83, 0x400, v10
	s_waitcnt vmcnt(22)
	ds_write2_b32 v10, v156, v157 offset1:66
	s_waitcnt vmcnt(20)
	ds_write2_b32 v10, v158, v159 offset0:132 offset1:198
	s_waitcnt vmcnt(18)
	ds_write2_b32 v83, v160, v161 offset0:8 offset1:74
	s_waitcnt vmcnt(16)
	ds_write2_b32 v83, v162, v163 offset0:140 offset1:206
	v_add_u32_e32 v10, 0x840, v10
	v_add_u32_e32 v83, 0x400, v10
	s_waitcnt vmcnt(14)
	ds_write2_b32 v10, v164, v165 offset1:66
	s_waitcnt vmcnt(12)
	ds_write2_b32 v10, v166, v167 offset0:132 offset1:198
	s_waitcnt vmcnt(10)
	ds_write2_b32 v83, v168, v169 offset0:8 offset1:74
	s_waitcnt vmcnt(8)
	ds_write2_b32 v83, v170, v171 offset0:140 offset1:206
	v_add_u32_e32 v10, 0x840, v10
	v_add_u32_e32 v83, 0x400, v10
	s_waitcnt vmcnt(6)
	ds_write2_b32 v10, v172, v173 offset1:66
	s_waitcnt vmcnt(4)
	ds_write2_b32 v10, v174, v175 offset0:132 offset1:198
	s_waitcnt vmcnt(2)
	ds_write2_b32 v83, v176, v177 offset0:8 offset1:74
	s_waitcnt vmcnt(0)
	ds_write2_b32 v83, v178, v179 offset0:140 offset1:206
	v_add_u32_e32 v10, 0x840, v10
	s_waitcnt lgkmcnt(0)
	ds_read2_b32 v[6:7], v45 offset1:8
	s_lshl_b32 s6, s8, 1
	ds_read2_b32 v[30:31], v45 offset0:33 offset1:41
	s_add_u32 s6, s79, s6
	s_addc_u32 s7, s80, 0
	v_lshlrev_b32_e32 v10, 1, v12
	ds_read2_b32 v[32:33], v45 offset0:66 offset1:74
	v_lshl_add_u64 v[2:3], s[6:7], 0, v[10:11]
	ds_read2_b32 v[34:35], v45 offset0:99 offset1:107
	v_lshl_add_u64 v[8:9], v[2:3], 0, s[34:35]
	s_waitcnt lgkmcnt(3)
	v_bfe_u32 v2, v6, 16, 1
	v_add3_u32 v2, v6, v2, s53
	s_waitcnt lgkmcnt(2)
	v_bfe_u32 v3, v30, 16, 1
	ds_read2_b32 v[36:37], v45 offset0:132 offset1:140
	v_lshrrev_b32_e32 v2, 16, v2
	v_add3_u32 v3, v30, v3, s53
	ds_read2_b32 v[38:39], v45 offset0:165 offset1:173
	v_and_or_b32 v2, v3, s54, v2
	s_waitcnt lgkmcnt(3)
	v_bfe_u32 v3, v32, 16, 1
	v_add3_u32 v3, v32, v3, s53
	s_waitcnt lgkmcnt(2)
	v_bfe_u32 v4, v34, 16, 1
	ds_read2_b32 v[40:41], v45 offset0:198 offset1:206
	v_lshrrev_b32_e32 v3, 16, v3
	v_add3_u32 v4, v34, v4, s53
	ds_read2_b32 v[80:81], v45 offset0:231 offset1:239
	v_and_or_b32 v3, v4, s54, v3
	s_waitcnt lgkmcnt(3)
	v_bfe_u32 v4, v36, 16, 1
	v_add3_u32 v4, v36, v4, s53
	s_waitcnt lgkmcnt(2)
	v_bfe_u32 v5, v38, 16, 1
	v_lshrrev_b32_e32 v4, 16, v4
	v_add3_u32 v5, v38, v5, s53
	v_and_or_b32 v4, v5, s54, v4
	s_waitcnt lgkmcnt(1)
	v_bfe_u32 v5, v40, 16, 1
	v_add3_u32 v5, v40, v5, s53
	s_waitcnt lgkmcnt(0)
	v_bfe_u32 v6, v80, 16, 1
	v_lshrrev_b32_e32 v5, 16, v5
	v_add3_u32 v6, v80, v6, s53
	v_and_or_b32 v5, v6, s54, v5
	v_or_b32_e32 v6, s5, v44
	v_lshlrev_b32_e32 v10, 11, v6
	v_lshl_add_u64 v[82:83], v[8:9], 0, v[10:11]
	global_store_dwordx4 v[82:83], v[2:5], off
	v_bfe_u32 v6, v81, 16, 1
	v_or_b32_e32 v10, s5, v46
	v_bfe_u32 v2, v7, 16, 1
	v_add3_u32 v2, v7, v2, s53
	v_bfe_u32 v3, v31, 16, 1
	v_lshrrev_b32_e32 v2, 16, v2
	v_add3_u32 v3, v31, v3, s53
	v_and_or_b32 v2, v3, s54, v2
	v_bfe_u32 v3, v33, 16, 1
	v_add3_u32 v3, v33, v3, s53
	v_bfe_u32 v4, v35, 16, 1
	v_lshrrev_b32_e32 v3, 16, v3
	v_add3_u32 v4, v35, v4, s53
	v_and_or_b32 v3, v4, s54, v3
	v_bfe_u32 v4, v37, 16, 1
	v_add3_u32 v4, v37, v4, s53
	v_bfe_u32 v5, v39, 16, 1
	v_lshrrev_b32_e32 v4, 16, v4
	v_add3_u32 v5, v39, v5, s53
	v_and_or_b32 v4, v5, s54, v4
	v_bfe_u32 v5, v41, 16, 1
	v_add3_u32 v5, v41, v5, s53
	v_lshrrev_b32_e32 v5, 16, v5
	v_add3_u32 v6, v81, v6, s53
	v_lshlrev_b32_e32 v10, 11, v10
	v_and_or_b32 v5, v6, s54, v5
	ds_read2_b32 v[6:7], v45 offset0:16 offset1:24
	v_lshl_add_u64 v[30:31], v[8:9], 0, v[10:11]
	global_store_dwordx4 v[30:31], v[2:5], off
	ds_read2_b32 v[30:31], v45 offset0:49 offset1:57
	ds_read2_b32 v[32:33], v45 offset0:82 offset1:90
	ds_read2_b32 v[34:35], v45 offset0:115 offset1:123
	s_waitcnt lgkmcnt(3)
	v_bfe_u32 v2, v6, 16, 1
	v_add3_u32 v2, v6, v2, s53
	s_waitcnt lgkmcnt(2)
	v_bfe_u32 v3, v30, 16, 1
	ds_read2_b32 v[36:37], v45 offset0:148 offset1:156
	v_lshrrev_b32_e32 v2, 16, v2
	v_add3_u32 v3, v30, v3, s53
	ds_read2_b32 v[38:39], v45 offset0:181 offset1:189
	v_and_or_b32 v2, v3, s54, v2
	s_waitcnt lgkmcnt(3)
	v_bfe_u32 v3, v32, 16, 1
	v_add3_u32 v3, v32, v3, s53
	s_waitcnt lgkmcnt(2)
	v_bfe_u32 v4, v34, 16, 1
	ds_read2_b32 v[40:41], v45 offset0:214 offset1:222
	v_lshrrev_b32_e32 v3, 16, v3
	v_add3_u32 v4, v34, v4, s53
	ds_read2_b32 v[80:81], v45 offset0:247 offset1:255
	v_and_or_b32 v3, v4, s54, v3
	s_waitcnt lgkmcnt(3)
	v_bfe_u32 v4, v36, 16, 1
	v_add3_u32 v4, v36, v4, s53
	s_waitcnt lgkmcnt(2)
	v_bfe_u32 v5, v38, 16, 1
	v_lshrrev_b32_e32 v4, 16, v4
	v_add3_u32 v5, v38, v5, s53
	v_and_or_b32 v4, v5, s54, v4
	s_waitcnt lgkmcnt(1)
	v_bfe_u32 v5, v40, 16, 1
	v_add3_u32 v5, v40, v5, s53
	s_waitcnt lgkmcnt(0)
	v_bfe_u32 v6, v80, 16, 1
	v_lshrrev_b32_e32 v5, 16, v5
	v_add3_u32 v6, v80, v6, s53
	v_and_or_b32 v5, v6, s54, v5
	v_or_b32_e32 v6, s5, v47
	v_lshlrev_b32_e32 v10, 11, v6
	v_lshl_add_u64 v[82:83], v[8:9], 0, v[10:11]
	global_store_dwordx4 v[82:83], v[2:5], off
	v_bfe_u32 v6, v81, 16, 1
	v_add3_u32 v6, v81, v6, s53
	v_bfe_u32 v2, v7, 16, 1
	v_add3_u32 v2, v7, v2, s53
	v_bfe_u32 v3, v31, 16, 1
	v_lshrrev_b32_e32 v2, 16, v2
	v_add3_u32 v3, v31, v3, s53
	v_and_or_b32 v2, v3, s54, v2
	v_bfe_u32 v3, v33, 16, 1
	v_add3_u32 v3, v33, v3, s53
	v_bfe_u32 v4, v35, 16, 1
	v_lshrrev_b32_e32 v3, 16, v3
	v_add3_u32 v4, v35, v4, s53
	v_and_or_b32 v3, v4, s54, v3
	v_bfe_u32 v4, v37, 16, 1
	v_add3_u32 v4, v37, v4, s53
	v_bfe_u32 v5, v39, 16, 1
	v_lshrrev_b32_e32 v4, 16, v4
	v_add3_u32 v5, v39, v5, s53
	v_and_or_b32 v4, v5, s54, v4
	v_bfe_u32 v5, v41, 16, 1
	v_add3_u32 v5, v41, v5, s53
	v_lshrrev_b32_e32 v5, 16, v5
	v_and_or_b32 v5, v6, s54, v5
	v_or_b32_e32 v6, s5, v48
	v_lshlrev_b32_e32 v10, 11, v6
	v_lshl_add_u64 v[6:7], v[8:9], 0, v[10:11]
	global_store_dwordx4 v[6:7], v[2:5], off
	s_waitcnt lgkmcnt(0)

.LBB0_48:
	v_lshl_add_u64 v[32:33], v[30:31], 0, s[8:9]
	v_add_co_u32_e32 v80, vcc, 0x2000, v32
	global_load_dword v148, v[32:33], off nt
	s_nop 0
	v_addc_co_u32_e32 v81, vcc, 0, v33, vcc
	v_add_co_u32_e32 v82, vcc, 0x4000, v32
	global_load_dword v149, v[80:81], off nt
	s_nop 0
	v_addc_co_u32_e32 v83, vcc, 0, v33, vcc
	v_add_co_u32_e32 v32, vcc, 0x6000, v32
	v_lshl_add_u64 v[34:35], v[8:9], 0, s[8:9]
	v_lshl_add_u64 v[36:37], v[6:7], 0, s[8:9]
	v_addc_co_u32_e32 v33, vcc, 0, v33, vcc
	v_lshl_add_u64 v[38:39], v[4:5], 0, s[8:9]
	v_lshl_add_u64 v[40:41], v[2:3], 0, s[8:9]
	global_load_dword v150, v[82:83], off nt
	s_nop 0
	global_load_dword v151, v[32:33], off nt
	s_nop 0
	global_load_dword v152, v[34:35], off nt
	s_nop 0
	global_load_dword v153, v[36:37], off nt
	global_load_dword v154, v[38:39], off nt
	s_nop 0
	global_load_dword v155, v[40:41], off nt
	s_add_u32 s8, s8, 0x10000
	s_addc_u32 s9, s9, 0
	v_lshl_add_u64 v[32:33], v[30:31], 0, s[8:9]
	v_add_co_u32_e32 v80, vcc, 0x2000, v32
	global_load_dword v156, v[32:33], off nt
	s_nop 0
	v_addc_co_u32_e32 v81, vcc, 0, v33, vcc
	v_add_co_u32_e32 v82, vcc, 0x4000, v32
	global_load_dword v157, v[80:81], off nt
	s_nop 0
	v_addc_co_u32_e32 v83, vcc, 0, v33, vcc
	v_add_co_u32_e32 v32, vcc, 0x6000, v32
	v_lshl_add_u64 v[34:35], v[8:9], 0, s[8:9]
	v_lshl_add_u64 v[36:37], v[6:7], 0, s[8:9]
	v_addc_co_u32_e32 v33, vcc, 0, v33, vcc
	v_lshl_add_u64 v[38:39], v[4:5], 0, s[8:9]
	v_lshl_add_u64 v[40:41], v[2:3], 0, s[8:9]
	global_load_dword v158, v[82:83], off nt
	s_nop 0
	global_load_dword v159, v[32:33], off nt
	s_nop 0
	global_load_dword v160, v[34:35], off nt
	s_nop 0
	global_load_dword v161, v[36:37], off nt
	global_load_dword v162, v[38:39], off nt
	s_nop 0
	global_load_dword v163, v[40:41], off nt
	s_add_u32 s8, s8, 0x10000
	s_addc_u32 s9, s9, 0
	v_lshl_add_u64 v[32:33], v[30:31], 0, s[8:9]
	v_add_co_u32_e32 v80, vcc, 0x2000, v32
	global_load_dword v164, v[32:33], off nt
	s_nop 0
	v_addc_co_u32_e32 v81, vcc, 0, v33, vcc
	v_add_co_u32_e32 v82, vcc, 0x4000, v32
	global_load_dword v165, v[80:81], off nt
	s_nop 0
	v_addc_co_u32_e32 v83, vcc, 0, v33, vcc
	v_add_co_u32_e32 v32, vcc, 0x6000, v32
	v_lshl_add_u64 v[34:35], v[8:9], 0, s[8:9]
	v_lshl_add_u64 v[36:37], v[6:7], 0, s[8:9]
	v_addc_co_u32_e32 v33, vcc, 0, v33, vcc
	v_lshl_add_u64 v[38:39], v[4:5], 0, s[8:9]
	v_lshl_add_u64 v[40:41], v[2:3], 0, s[8:9]
	global_load_dword v166, v[82:83], off nt
	s_nop 0
	global_load_dword v167, v[32:33], off nt
	s_nop 0
	global_load_dword v168, v[34:35], off nt
	s_nop 0
	global_load_dword v169, v[36:37], off nt
	global_load_dword v170, v[38:39], off nt
	s_nop 0
	global_load_dword v171, v[40:41], off nt
	s_add_u32 s8, s8, 0x10000
	s_addc_u32 s9, s9, 0
	v_lshl_add_u64 v[32:33], v[30:31], 0, s[8:9]
	v_add_co_u32_e32 v80, vcc, 0x2000, v32
	global_load_dword v172, v[32:33], off nt
	s_nop 0
	v_addc_co_u32_e32 v81, vcc, 0, v33, vcc
	v_add_co_u32_e32 v82, vcc, 0x4000, v32
	global_load_dword v173, v[80:81], off nt
	s_nop 0
	v_addc_co_u32_e32 v83, vcc, 0, v33, vcc
	v_add_co_u32_e32 v32, vcc, 0x6000, v32
	v_lshl_add_u64 v[34:35], v[8:9], 0, s[8:9]
	v_lshl_add_u64 v[36:37], v[6:7], 0, s[8:9]
	v_addc_co_u32_e32 v33, vcc, 0, v33, vcc
	v_lshl_add_u64 v[38:39], v[4:5], 0, s[8:9]
	v_lshl_add_u64 v[40:41], v[2:3], 0, s[8:9]
	global_load_dword v174, v[82:83], off nt
	s_nop 0
	global_load_dword v175, v[32:33], off nt
	s_nop 0
	global_load_dword v176, v[34:35], off nt
	s_nop 0
	global_load_dword v177, v[36:37], off nt
	global_load_dword v178, v[38:39], off nt
	s_nop 0
	global_load_dword v179, v[40:41], off nt
	s_add_u32 s8, s8, 0x10000
	s_addc_u32 s9, s9, 0
	v_add_u32_e32 v37, 0x400, v10
	s_waitcnt vmcnt(30)
	ds_write2_b32 v10, v148, v149 offset1:66
	s_waitcnt vmcnt(28)
	ds_write2_b32 v10, v150, v151 offset0:132 offset1:198
	s_waitcnt vmcnt(26)
	ds_write2_b32 v37, v152, v153 offset0:8 offset1:74
	s_waitcnt vmcnt(24)
	ds_write2_b32 v37, v154, v155 offset0:140 offset1:206
	v_add_u32_e32 v10, 0x840, v10
	v_add_u32_e32 v37, 0x400, v10
	s_waitcnt vmcnt(22)
	ds_write2_b32 v10, v156, v157 offset1:66
	s_waitcnt vmcnt(20)
	ds_write2_b32 v10, v158, v159 offset0:132 offset1:198
	s_waitcnt vmcnt(18)
	ds_write2_b32 v37, v160, v161 offset0:8 offset1:74
	s_waitcnt vmcnt(16)
	ds_write2_b32 v37, v162, v163 offset0:140 offset1:206
	v_add_u32_e32 v10, 0x840, v10
	v_add_u32_e32 v37, 0x400, v10
	s_waitcnt vmcnt(14)
	ds_write2_b32 v10, v164, v165 offset1:66
	s_waitcnt vmcnt(12)
	ds_write2_b32 v10, v166, v167 offset0:132 offset1:198
	s_waitcnt vmcnt(10)
	ds_write2_b32 v37, v168, v169 offset0:8 offset1:74
	s_waitcnt vmcnt(8)
	ds_write2_b32 v37, v170, v171 offset0:140 offset1:206
	v_add_u32_e32 v10, 0x840, v10
	v_add_u32_e32 v37, 0x400, v10
	s_waitcnt vmcnt(6)
	ds_write2_b32 v10, v172, v173 offset1:66
	s_waitcnt vmcnt(4)
	ds_write2_b32 v10, v174, v175 offset0:132 offset1:198
	s_waitcnt vmcnt(2)
	ds_write2_b32 v37, v176, v177 offset0:8 offset1:74
	s_waitcnt vmcnt(0)
	ds_write2_b32 v37, v178, v179 offset0:140 offset1:206
	v_add_u32_e32 v10, 0x840, v10
	s_waitcnt lgkmcnt(0)
	ds_read2_b32 v[6:7], v45 offset1:8
	ds_read2_b32 v[30:31], v45 offset0:33 offset1:41
	ds_read2_b32 v[32:33], v45 offset0:66 offset1:74
	ds_read2_b32 v[34:35], v45 offset0:99 offset1:107
	ds_read2_b32 v[36:37], v45 offset0:132 offset1:140
	s_waitcnt lgkmcnt(4)
	v_bfe_u32 v2, v6, 16, 1
	v_add3_u32 v2, v6, v2, s53
	s_waitcnt lgkmcnt(3)
	v_bfe_u32 v3, v30, 16, 1
	v_lshrrev_b32_e32 v2, 16, v2
	v_add3_u32 v3, v30, v3, s53
	ds_read2_b32 v[38:39], v45 offset0:165 offset1:173
	v_and_or_b32 v2, v3, s54, v2
	s_waitcnt lgkmcnt(3)
	v_bfe_u32 v3, v32, 16, 1
	v_add3_u32 v3, v32, v3, s53
	s_waitcnt lgkmcnt(2)
	v_bfe_u32 v4, v34, 16, 1
	ds_read2_b32 v[40:41], v45 offset0:198 offset1:206
	s_lshl_b32 s5, s5, 5
	v_lshrrev_b32_e32 v3, 16, v3
	v_add3_u32 v4, v34, v4, s53
	ds_read2_b32 v[80:81], v45 offset0:231 offset1:239
	s_and_b32 s5, s5, 0x3e0
	v_and_or_b32 v3, v4, s54, v3
	s_waitcnt lgkmcnt(3)
	v_bfe_u32 v4, v36, 16, 1
	s_and_b64 s[6:7], s[6:7], exec
	v_add3_u32 v4, v36, v4, s53
	s_waitcnt lgkmcnt(2)
	v_bfe_u32 v5, v38, 16, 1
	s_cselect_b32 s6, s57, 0xb00000
	v_lshrrev_b32_e32 v4, 16, v4
	v_add3_u32 v5, v38, v5, s53
	s_add_u32 s6, s79, s6
	v_and_or_b32 v4, v5, s54, v4
	s_waitcnt lgkmcnt(1)
	v_bfe_u32 v5, v40, 16, 1
	s_addc_u32 s7, s80, 0
	s_lshl_b32 s8, s36, 1
	v_add3_u32 v5, v40, v5, s53
	s_waitcnt lgkmcnt(0)
	v_bfe_u32 v6, v80, 16, 1
	s_add_u32 s6, s6, s8
	v_lshrrev_b32_e32 v5, 16, v5
	v_add3_u32 v6, v80, v6, s53
	s_addc_u32 s7, s7, 0
	v_lshlrev_b32_e32 v10, 1, v12
	v_and_or_b32 v5, v6, s54, v5
	v_or_b32_e32 v6, s5, v44
	v_lshl_add_u64 v[8:9], s[6:7], 0, v[10:11]
	v_mul_u32_u24_e32 v10, 0x1600, v6
	v_lshl_add_u64 v[82:83], v[8:9], 0, v[10:11]
	global_store_dwordx4 v[82:83], v[2:5], off
	v_bfe_u32 v6, v81, 16, 1
	v_or_b32_e32 v10, s5, v46
	v_bfe_u32 v2, v7, 16, 1
	v_add3_u32 v2, v7, v2, s53
	v_bfe_u32 v3, v31, 16, 1
	v_lshrrev_b32_e32 v2, 16, v2
	v_add3_u32 v3, v31, v3, s53
	v_and_or_b32 v2, v3, s54, v2
	v_bfe_u32 v3, v33, 16, 1
	v_add3_u32 v3, v33, v3, s53
	v_bfe_u32 v4, v35, 16, 1
	v_lshrrev_b32_e32 v3, 16, v3
	v_add3_u32 v4, v35, v4, s53
	v_and_or_b32 v3, v4, s54, v3
	v_bfe_u32 v4, v37, 16, 1
	v_add3_u32 v4, v37, v4, s53
	v_bfe_u32 v5, v39, 16, 1
	v_lshrrev_b32_e32 v4, 16, v4
	v_add3_u32 v5, v39, v5, s53
	v_and_or_b32 v4, v5, s54, v4
	v_bfe_u32 v5, v41, 16, 1
	v_add3_u32 v5, v41, v5, s53
	v_lshrrev_b32_e32 v5, 16, v5
	v_add3_u32 v6, v81, v6, s53
	v_mul_u32_u24_e32 v10, 0x1600, v10
	v_and_or_b32 v5, v6, s54, v5
	ds_read2_b32 v[6:7], v45 offset0:16 offset1:24
	v_lshl_add_u64 v[30:31], v[8:9], 0, v[10:11]
	global_store_dwordx4 v[30:31], v[2:5], off
	ds_read2_b32 v[30:31], v45 offset0:49 offset1:57
	ds_read2_b32 v[32:33], v45 offset0:82 offset1:90
	ds_read2_b32 v[34:35], v45 offset0:115 offset1:123
	s_waitcnt lgkmcnt(3)
	v_bfe_u32 v2, v6, 16, 1
	v_add3_u32 v2, v6, v2, s53
	s_waitcnt lgkmcnt(2)
	v_bfe_u32 v3, v30, 16, 1
	ds_read2_b32 v[36:37], v45 offset0:148 offset1:156
	v_lshrrev_b32_e32 v2, 16, v2
	v_add3_u32 v3, v30, v3, s53
	ds_read2_b32 v[38:39], v45 offset0:181 offset1:189
	v_and_or_b32 v2, v3, s54, v2
	s_waitcnt lgkmcnt(3)
	v_bfe_u32 v3, v32, 16, 1
	v_add3_u32 v3, v32, v3, s53
	s_waitcnt lgkmcnt(2)
	v_bfe_u32 v4, v34, 16, 1
	ds_read2_b32 v[40:41], v45 offset0:214 offset1:222
	v_lshrrev_b32_e32 v3, 16, v3
	v_add3_u32 v4, v34, v4, s53
	ds_read2_b32 v[80:81], v45 offset0:247 offset1:255
	v_and_or_b32 v3, v4, s54, v3
	s_waitcnt lgkmcnt(3)
	v_bfe_u32 v4, v36, 16, 1
	v_add3_u32 v4, v36, v4, s53
	s_waitcnt lgkmcnt(2)
	v_bfe_u32 v5, v38, 16, 1
	v_lshrrev_b32_e32 v4, 16, v4
	v_add3_u32 v5, v38, v5, s53
	v_and_or_b32 v4, v5, s54, v4
	s_waitcnt lgkmcnt(1)
	v_bfe_u32 v5, v40, 16, 1
	v_add3_u32 v5, v40, v5, s53
	s_waitcnt lgkmcnt(0)
	v_bfe_u32 v6, v80, 16, 1
	v_lshrrev_b32_e32 v5, 16, v5
	v_add3_u32 v6, v80, v6, s53
	v_and_or_b32 v5, v6, s54, v5
	v_or_b32_e32 v6, s5, v47
	v_mul_u32_u24_e32 v10, 0x1600, v6
	v_lshl_add_u64 v[82:83], v[8:9], 0, v[10:11]
	global_store_dwordx4 v[82:83], v[2:5], off
	v_bfe_u32 v6, v81, 16, 1
	v_add3_u32 v6, v81, v6, s53
	v_bfe_u32 v2, v7, 16, 1
	v_add3_u32 v2, v7, v2, s53
	v_bfe_u32 v3, v31, 16, 1
	v_lshrrev_b32_e32 v2, 16, v2
	v_add3_u32 v3, v31, v3, s53
	v_and_or_b32 v2, v3, s54, v2
	v_bfe_u32 v3, v33, 16, 1
	v_add3_u32 v3, v33, v3, s53
	v_bfe_u32 v4, v35, 16, 1
	v_lshrrev_b32_e32 v3, 16, v3
	v_add3_u32 v4, v35, v4, s53
	v_and_or_b32 v3, v4, s54, v3
	v_bfe_u32 v4, v37, 16, 1
	v_add3_u32 v4, v37, v4, s53
	v_bfe_u32 v5, v39, 16, 1
	v_lshrrev_b32_e32 v4, 16, v4
	v_add3_u32 v5, v39, v5, s53
	v_and_or_b32 v4, v5, s54, v4
	v_bfe_u32 v5, v41, 16, 1
	v_add3_u32 v5, v41, v5, s53
	v_lshrrev_b32_e32 v5, 16, v5
	v_and_or_b32 v5, v6, s54, v5
	v_or_b32_e32 v6, s5, v48
	v_mul_u32_u24_e32 v10, 0x1600, v6
	v_lshl_add_u64 v[6:7], v[8:9], 0, v[10:11]
	global_store_dwordx4 v[6:7], v[2:5], off
	s_waitcnt lgkmcnt(0)

.LBB0_53:
	v_lshl_add_u64 v[38:39], v[36:37], 0, s[8:9]
	v_lshl_add_u64 v[40:41], v[34:35], 0, s[8:9]
	v_lshl_add_u64 v[80:81], v[32:33], 0, s[8:9]
	v_lshl_add_u64 v[82:83], v[30:31], 0, s[8:9]
	v_lshl_add_u64 v[84:85], v[8:9], 0, s[8:9]
	v_lshl_add_u64 v[86:87], v[6:7], 0, s[8:9]
	v_lshl_add_u64 v[88:89], v[4:5], 0, s[8:9]
	v_lshl_add_u64 v[90:91], v[2:3], 0, s[8:9]
	global_load_dword v148, v[38:39], off nt
	s_nop 0
	global_load_dword v149, v[40:41], off nt
	global_load_dword v150, v[80:81], off nt
	s_nop 0
	global_load_dword v151, v[82:83], off nt
	global_load_dword v152, v[84:85], off nt
	global_load_dword v153, v[86:87], off nt
	global_load_dword v154, v[88:89], off nt
	s_nop 0
	global_load_dword v155, v[90:91], off nt
	s_add_u32 s8, s8, 0x58000
	s_addc_u32 s9, s9, 0
	v_lshl_add_u64 v[38:39], v[36:37], 0, s[8:9]
	v_lshl_add_u64 v[40:41], v[34:35], 0, s[8:9]
	v_lshl_add_u64 v[80:81], v[32:33], 0, s[8:9]
	v_lshl_add_u64 v[82:83], v[30:31], 0, s[8:9]
	v_lshl_add_u64 v[84:85], v[8:9], 0, s[8:9]
	v_lshl_add_u64 v[86:87], v[6:7], 0, s[8:9]
	v_lshl_add_u64 v[88:89], v[4:5], 0, s[8:9]
	v_lshl_add_u64 v[90:91], v[2:3], 0, s[8:9]
	global_load_dword v156, v[38:39], off nt
	s_nop 0
	global_load_dword v157, v[40:41], off nt
	global_load_dword v158, v[80:81], off nt
	s_nop 0
	global_load_dword v159, v[82:83], off nt
	global_load_dword v160, v[84:85], off nt
	global_load_dword v161, v[86:87], off nt
	global_load_dword v162, v[88:89], off nt
	s_nop 0
	global_load_dword v163, v[90:91], off nt
	s_add_u32 s8, s8, 0x58000
	s_addc_u32 s9, s9, 0
	v_lshl_add_u64 v[38:39], v[36:37], 0, s[8:9]
	v_lshl_add_u64 v[40:41], v[34:35], 0, s[8:9]
	v_lshl_add_u64 v[80:81], v[32:33], 0, s[8:9]
	v_lshl_add_u64 v[82:83], v[30:31], 0, s[8:9]
	v_lshl_add_u64 v[84:85], v[8:9], 0, s[8:9]
	v_lshl_add_u64 v[86:87], v[6:7], 0, s[8:9]
	v_lshl_add_u64 v[88:89], v[4:5], 0, s[8:9]
	v_lshl_add_u64 v[90:91], v[2:3], 0, s[8:9]
	global_load_dword v164, v[38:39], off nt
	s_nop 0
	global_load_dword v165, v[40:41], off nt
	global_load_dword v166, v[80:81], off nt
	s_nop 0
	global_load_dword v167, v[82:83], off nt
	global_load_dword v168, v[84:85], off nt
	global_load_dword v169, v[86:87], off nt
	global_load_dword v170, v[88:89], off nt
	s_nop 0
	global_load_dword v171, v[90:91], off nt
	s_add_u32 s8, s8, 0x58000
	s_addc_u32 s9, s9, 0
	v_lshl_add_u64 v[38:39], v[36:37], 0, s[8:9]
	v_lshl_add_u64 v[40:41], v[34:35], 0, s[8:9]
	v_lshl_add_u64 v[80:81], v[32:33], 0, s[8:9]
	v_lshl_add_u64 v[82:83], v[30:31], 0, s[8:9]
	v_lshl_add_u64 v[84:85], v[8:9], 0, s[8:9]
	v_lshl_add_u64 v[86:87], v[6:7], 0, s[8:9]
	v_lshl_add_u64 v[88:89], v[4:5], 0, s[8:9]
	v_lshl_add_u64 v[90:91], v[2:3], 0, s[8:9]
	global_load_dword v172, v[38:39], off nt
	s_nop 0
	global_load_dword v173, v[40:41], off nt
	global_load_dword v174, v[80:81], off nt
	s_nop 0
	global_load_dword v175, v[82:83], off nt
	global_load_dword v176, v[84:85], off nt
	global_load_dword v177, v[86:87], off nt
	global_load_dword v178, v[88:89], off nt
	s_nop 0
	global_load_dword v179, v[90:91], off nt
	s_add_u32 s8, s8, 0x58000
	s_addc_u32 s9, s9, 0
	v_add_u32_e32 v83, 0x400, v10
	s_waitcnt vmcnt(30)
	ds_write2_b32 v10, v148, v149 offset1:66
	s_waitcnt vmcnt(28)
	ds_write2_b32 v10, v150, v151 offset0:132 offset1:198
	s_waitcnt vmcnt(26)
	ds_write2_b32 v83, v152, v153 offset0:8 offset1:74
	s_waitcnt vmcnt(24)
	ds_write2_b32 v83, v154, v155 offset0:140 offset1:206
	v_add_u32_e32 v10, 0x840, v10
	v_add_u32_e32 v83, 0x400, v10
	s_waitcnt vmcnt(22)
	ds_write2_b32 v10, v156, v157 offset1:66
	s_waitcnt vmcnt(20)
	ds_write2_b32 v10, v158, v159 offset0:132 offset1:198
	s_waitcnt vmcnt(18)
	ds_write2_b32 v83, v160, v161 offset0:8 offset1:74
	s_waitcnt vmcnt(16)
	ds_write2_b32 v83, v162, v163 offset0:140 offset1:206
	v_add_u32_e32 v10, 0x840, v10
	v_add_u32_e32 v83, 0x400, v10
	s_waitcnt vmcnt(14)
	ds_write2_b32 v10, v164, v165 offset1:66
	s_waitcnt vmcnt(12)
	ds_write2_b32 v10, v166, v167 offset0:132 offset1:198
	s_waitcnt vmcnt(10)
	ds_write2_b32 v83, v168, v169 offset0:8 offset1:74
	s_waitcnt vmcnt(8)
	ds_write2_b32 v83, v170, v171 offset0:140 offset1:206
	v_add_u32_e32 v10, 0x840, v10
	v_add_u32_e32 v83, 0x400, v10
	s_waitcnt vmcnt(6)
	ds_write2_b32 v10, v172, v173 offset1:66
	s_waitcnt vmcnt(4)
	ds_write2_b32 v10, v174, v175 offset0:132 offset1:198
	s_waitcnt vmcnt(2)
	ds_write2_b32 v83, v176, v177 offset0:8 offset1:74
	s_waitcnt vmcnt(0)
	ds_write2_b32 v83, v178, v179 offset0:140 offset1:206
	v_add_u32_e32 v10, 0x840, v10
	s_waitcnt lgkmcnt(0)
	ds_read2_b32 v[6:7], v45 offset1:8
	ds_read2_b32 v[30:31], v45 offset0:33 offset1:41
	ds_read2_b32 v[32:33], v45 offset0:66 offset1:74
	ds_read2_b32 v[34:35], v45 offset0:99 offset1:107
	ds_read2_b32 v[36:37], v45 offset0:132 offset1:140
	s_waitcnt lgkmcnt(4)
	v_bfe_u32 v2, v6, 16, 1
	v_add3_u32 v2, v6, v2, s53
	s_waitcnt lgkmcnt(3)
	v_bfe_u32 v3, v30, 16, 1
	v_lshrrev_b32_e32 v2, 16, v2
	v_add3_u32 v3, v30, v3, s53
	ds_read2_b32 v[38:39], v45 offset0:165 offset1:173
	v_and_or_b32 v2, v3, s54, v2
	s_waitcnt lgkmcnt(3)
	v_bfe_u32 v3, v32, 16, 1
	v_add3_u32 v3, v32, v3, s53
	s_waitcnt lgkmcnt(2)
	v_bfe_u32 v4, v34, 16, 1
	ds_read2_b32 v[40:41], v45 offset0:198 offset1:206
	s_and_b64 s[6:7], s[6:7], exec
	v_lshrrev_b32_e32 v3, 16, v3
	v_add3_u32 v4, v34, v4, s53
	ds_read2_b32 v[80:81], v45 offset0:231 offset1:239
	s_cselect_b32 s6, 0x1500000, 0
	v_and_or_b32 v3, v4, s54, v3
	s_waitcnt lgkmcnt(3)
	v_bfe_u32 v4, v36, 16, 1
	s_add_u32 s6, s79, s6
	v_add3_u32 v4, v36, v4, s53
	s_waitcnt lgkmcnt(2)
	v_bfe_u32 v5, v38, 16, 1
	s_addc_u32 s7, s80, 0
	s_lshl_b64 s[4:5], s[4:5], 1
	v_lshrrev_b32_e32 v4, 16, v4
	v_add3_u32 v5, v38, v5, s53
	s_add_u32 s4, s6, s4
	v_and_or_b32 v4, v5, s54, v4
	s_waitcnt lgkmcnt(1)
	v_bfe_u32 v5, v40, 16, 1
	v_or_b32_e32 v82, s28, v44
	s_addc_u32 s5, s7, s5
	v_lshlrev_b32_e32 v10, 1, v12
	v_add3_u32 v5, v40, v5, s53
	s_waitcnt lgkmcnt(0)
	v_bfe_u32 v6, v80, 16, 1
	v_ashrrev_i32_e32 v83, 31, v82
	v_lshl_add_u64 v[8:9], s[4:5], 0, v[10:11]
	v_lshrrev_b32_e32 v5, 16, v5
	v_add3_u32 v6, v80, v6, s53
	v_lshlrev_b64 v[82:83], 11, v[82:83]
	v_and_or_b32 v5, v6, s54, v5
	v_lshl_add_u64 v[82:83], v[8:9], 0, v[82:83]
	global_store_dwordx4 v[82:83], v[2:5], off
	v_bfe_u32 v6, v81, 16, 1
	v_add3_u32 v6, v81, v6, s53
	v_bfe_u32 v2, v7, 16, 1
	v_add3_u32 v2, v7, v2, s53
	v_bfe_u32 v3, v31, 16, 1
	v_lshrrev_b32_e32 v2, 16, v2
	v_add3_u32 v3, v31, v3, s53
	v_and_or_b32 v2, v3, s54, v2
	v_bfe_u32 v3, v33, 16, 1
	v_add3_u32 v3, v33, v3, s53
	v_bfe_u32 v4, v35, 16, 1
	v_lshrrev_b32_e32 v3, 16, v3
	v_add3_u32 v4, v35, v4, s53
	v_and_or_b32 v3, v4, s54, v3
	v_bfe_u32 v4, v37, 16, 1
	v_add3_u32 v4, v37, v4, s53
	v_bfe_u32 v5, v39, 16, 1
	v_lshrrev_b32_e32 v4, 16, v4
	v_add3_u32 v5, v39, v5, s53
	v_and_or_b32 v4, v5, s54, v4
	v_bfe_u32 v5, v41, 16, 1
	v_add3_u32 v5, v41, v5, s53
	v_lshrrev_b32_e32 v5, 16, v5
	v_and_or_b32 v5, v6, s54, v5
	v_or_b32_e32 v6, s28, v46
	v_ashrrev_i32_e32 v7, 31, v6
	v_lshlrev_b64 v[6:7], 11, v[6:7]
	ds_read2_b32 v[30:31], v45 offset0:16 offset1:24
	v_lshl_add_u64 v[6:7], v[8:9], 0, v[6:7]
	global_store_dwordx4 v[6:7], v[2:5], off
	ds_read2_b32 v[6:7], v45 offset0:49 offset1:57
	ds_read2_b32 v[32:33], v45 offset0:82 offset1:90
	ds_read2_b32 v[34:35], v45 offset0:115 offset1:123
	s_waitcnt lgkmcnt(3)
	v_bfe_u32 v2, v30, 16, 1
	v_add3_u32 v2, v30, v2, s53
	s_waitcnt lgkmcnt(2)
	v_bfe_u32 v3, v6, 16, 1
	ds_read2_b32 v[36:37], v45 offset0:148 offset1:156
	v_lshrrev_b32_e32 v2, 16, v2
	v_add3_u32 v3, v6, v3, s53
	ds_read2_b32 v[38:39], v45 offset0:181 offset1:189
	v_and_or_b32 v2, v3, s54, v2
	s_waitcnt lgkmcnt(3)
	v_bfe_u32 v3, v32, 16, 1
	v_add3_u32 v3, v32, v3, s53
	s_waitcnt lgkmcnt(2)
	v_bfe_u32 v4, v34, 16, 1
	ds_read2_b32 v[40:41], v45 offset0:214 offset1:222
	v_lshrrev_b32_e32 v3, 16, v3
	v_add3_u32 v4, v34, v4, s53
	ds_read2_b32 v[80:81], v45 offset0:247 offset1:255
	v_and_or_b32 v3, v4, s54, v3
	s_waitcnt lgkmcnt(3)
	v_bfe_u32 v4, v36, 16, 1
	v_add3_u32 v4, v36, v4, s53
	s_waitcnt lgkmcnt(2)
	v_bfe_u32 v5, v38, 16, 1
	v_lshrrev_b32_e32 v4, 16, v4
	v_add3_u32 v5, v38, v5, s53
	v_and_or_b32 v4, v5, s54, v4
	s_waitcnt lgkmcnt(1)
	v_bfe_u32 v5, v40, 16, 1
	v_or_b32_e32 v82, s28, v47
	v_add3_u32 v5, v40, v5, s53
	s_waitcnt lgkmcnt(0)
	v_bfe_u32 v6, v80, 16, 1
	v_ashrrev_i32_e32 v83, 31, v82
	v_lshrrev_b32_e32 v5, 16, v5
	v_add3_u32 v6, v80, v6, s53
	v_lshlrev_b64 v[82:83], 11, v[82:83]
	v_and_or_b32 v5, v6, s54, v5
	v_lshl_add_u64 v[82:83], v[8:9], 0, v[82:83]
	global_store_dwordx4 v[82:83], v[2:5], off
	v_bfe_u32 v6, v81, 16, 1
	v_add3_u32 v6, v81, v6, s53
	v_bfe_u32 v2, v31, 16, 1
	v_add3_u32 v2, v31, v2, s53
	v_bfe_u32 v3, v7, 16, 1
	v_lshrrev_b32_e32 v2, 16, v2
	v_add3_u32 v3, v7, v3, s53
	v_and_or_b32 v2, v3, s54, v2
	v_bfe_u32 v3, v33, 16, 1
	v_add3_u32 v3, v33, v3, s53
	v_bfe_u32 v4, v35, 16, 1
	v_lshrrev_b32_e32 v3, 16, v3
	v_add3_u32 v4, v35, v4, s53
	v_and_or_b32 v3, v4, s54, v3
	v_bfe_u32 v4, v37, 16, 1
	v_add3_u32 v4, v37, v4, s53
	v_bfe_u32 v5, v39, 16, 1
	v_lshrrev_b32_e32 v4, 16, v4
	v_add3_u32 v5, v39, v5, s53
	v_and_or_b32 v4, v5, s54, v4
	v_bfe_u32 v5, v41, 16, 1
	v_add3_u32 v5, v41, v5, s53
	v_lshrrev_b32_e32 v5, 16, v5
	v_and_or_b32 v5, v6, s54, v5
	v_or_b32_e32 v6, s28, v48
	v_ashrrev_i32_e32 v7, 31, v6
	v_lshlrev_b64 v[6:7], 11, v[6:7]
	v_lshl_add_u64 v[6:7], v[8:9], 0, v[6:7]
	global_store_dwordx4 v[6:7], v[2:5], off
	s_waitcnt lgkmcnt(0)
